# attention inner loop: row-max via v_max3 without self-max canonicalisation, band-mask compares only in masked chunks
# baseline (speedup 1.0000x reference)
.LBB0_121:
	s_andn2_b64 vcc, exec, s[0:1]
	s_cbranch_vccnz .LBB0_123
	v_add_u32_e32 v216, 1, v3
	v_add_u32_e32 v215, 2, v3
	v_add_u32_e32 v213, 3, v3
	v_cmp_lt_i32_e64 s[0:1], v3, v211
	v_cmp_gt_u32_e64 s[42:43], v3, v210
	v_cmp_ge_u32_e64 s[44:45], v3, v210
	v_cmp_lt_i32_e64 s[50:51], v216, v211
	v_cmp_lt_i32_e64 s[46:47], v215, v211
	v_cmp_gt_u32_e64 s[52:53], v215, v210
	v_cmp_lt_i32_e64 s[48:49], v213, v211
	v_cmp_gt_u32_e64 s[56:57], v213, v210
	s_or_b64 vcc, s[0:1], s[42:43]
	v_cndmask_b32_e32 v136, v136, v191, vcc
	s_or_b64 vcc, s[50:51], s[44:45]
	v_cndmask_b32_e32 v137, v137, v191, vcc
	s_or_b64 vcc, s[46:47], s[52:53]
	v_cndmask_b32_e32 v138, v138, v191, vcc
	s_or_b64 vcc, s[48:49], s[56:57]
	v_cndmask_b32_e32 v139, v139, v191, vcc

.LBB0_125:
	s_andn2_b64 vcc, exec, s[0:1]
	s_cbranch_vccnz .LBB0_127
	v_add_u32_e32 v218, 16, v3
	v_add_u32_e32 v217, 17, v3
	v_add_u32_e32 v214, 18, v3
	v_add_u32_e32 v212, 19, v3
	v_cmp_lt_i32_e64 s[0:1], v218, v211
	v_cmp_gt_u32_e64 s[48:49], v218, v210
	v_cmp_lt_i32_e64 s[42:43], v217, v211
	v_cmp_gt_u32_e64 s[50:51], v217, v210
	v_cmp_lt_i32_e64 s[44:45], v214, v211
	v_cmp_gt_u32_e64 s[52:53], v214, v210
	v_cmp_lt_i32_e64 s[46:47], v212, v211
	v_cmp_gt_u32_e64 s[56:57], v212, v210
	s_or_b64 vcc, s[0:1], s[48:49]
	v_cndmask_b32_e32 v140, v140, v191, vcc
	s_or_b64 vcc, s[42:43], s[50:51]
	v_cndmask_b32_e32 v141, v141, v191, vcc
	s_or_b64 vcc, s[44:45], s[52:53]
	v_cndmask_b32_e32 v142, v142, v191, vcc
	s_or_b64 vcc, s[46:47], s[56:57]
	v_cndmask_b32_e32 v143, v143, v191, vcc
.LBB0_127:
	v_max3_f32 v5, v136, v137, v138
	s_nop 3
	v_max3_f32 v6, v139, v140, v141
	v_max_f32_e32 v7, v142, v143
	v_max3_f32 v5, v5, v6, v7
	v_add_f32_e32 v6, 0x41000000, v162
	v_cmp_gt_f32_e32 vcc, v5, v6
	s_cbranch_vccz .LBB0_129
	v_and_b32_e32 v7, 64, v192
	v_xor_b32_e32 v6, 16, v192
	v_add_u32_e32 v144, 64, v7
	v_cmp_lt_i32_e32 vcc, v6, v144
	v_xor_b32_e32 v145, 32, v192
	s_nop 0
	v_cndmask_b32_e32 v6, v192, v6, vcc
	v_lshlrev_b32_e32 v6, 2, v6
	ds_bpermute_b32 v6, v6, v5
	v_max_f32_e32 v5, v5, v5
	v_cmp_lt_i32_e32 vcc, v145, v144
	s_waitcnt lgkmcnt(0)
	v_max_f32_e32 v6, v6, v6
	v_max_f32_e32 v5, v5, v6
	v_cndmask_b32_e32 v6, v192, v145, vcc
	v_lshlrev_b32_e32 v6, 2, v6
	ds_bpermute_b32 v6, v6, v5
	s_waitcnt lgkmcnt(0)
	v_max3_f32 v5, v162, v5, v6
	v_sub_f32_e32 v6, v162, v5
	v_exp_f32_e32 v146, v6
	v_or_b32_e32 v6, v7, v167
	v_lshlrev_b32_e32 v7, 2, v6
	v_or_b32_e32 v145, 12, v7
	ds_bpermute_b32 v6, v7, v146
	ds_bpermute_b32 v144, v7, v146 offset:8
	ds_bpermute_b32 v145, v145, v146
	ds_bpermute_b32 v7, v7, v146 offset:4
	v_mov_b32_e32 v162, v5
	s_waitcnt lgkmcnt(1)
	v_pk_mul_f32 v[90:91], v[90:91], v[144:145]
	s_waitcnt lgkmcnt(0)
	v_pk_mul_f32 v[88:89], v[88:89], v[6:7]
	v_pk_mul_f32 v[86:87], v[86:87], v[144:145]
	v_pk_mul_f32 v[84:85], v[84:85], v[6:7]
	v_pk_mul_f32 v[82:83], v[82:83], v[144:145]
	v_pk_mul_f32 v[80:81], v[80:81], v[6:7]
	v_pk_mul_f32 v[78:79], v[78:79], v[144:145]
	v_pk_mul_f32 v[76:77], v[76:77], v[6:7]
	v_pk_mul_f32 v[94:95], v[94:95], v[144:145]
	v_pk_mul_f32 v[92:93], v[92:93], v[6:7]

.LBB0_137:
	v_max3_f32 v5, v136, v137, v138
	s_nop 3
	v_max3_f32 v6, v139, v140, v141
	v_max_f32_e32 v7, v142, v143
	v_max3_f32 v5, v5, v6, v7
	v_add_f32_e32 v6, 0x41000000, v163
	v_cmp_gt_f32_e32 vcc, v5, v6
	s_cbranch_vccz .LBB0_139
	v_and_b32_e32 v7, 64, v192
	v_xor_b32_e32 v6, 16, v192
	v_add_u32_e32 v144, 64, v7
	v_cmp_lt_i32_e32 vcc, v6, v144
	v_xor_b32_e32 v145, 32, v192
	s_nop 0
	v_cndmask_b32_e32 v6, v192, v6, vcc
	v_lshlrev_b32_e32 v6, 2, v6
	ds_bpermute_b32 v6, v6, v5
	v_max_f32_e32 v5, v5, v5
	v_cmp_lt_i32_e32 vcc, v145, v144
	s_waitcnt lgkmcnt(0)
	v_max_f32_e32 v6, v6, v6
	v_max_f32_e32 v5, v5, v6
	v_cndmask_b32_e32 v6, v192, v145, vcc
	v_lshlrev_b32_e32 v6, 2, v6
	ds_bpermute_b32 v6, v6, v5
	s_waitcnt lgkmcnt(0)
	v_max3_f32 v5, v163, v5, v6
	v_sub_f32_e32 v6, v163, v5
	v_exp_f32_e32 v146, v6
	v_or_b32_e32 v6, v7, v167
	v_lshlrev_b32_e32 v7, 2, v6
	v_or_b32_e32 v145, 12, v7
	ds_bpermute_b32 v6, v7, v146
	ds_bpermute_b32 v144, v7, v146 offset:8
	ds_bpermute_b32 v145, v145, v146
	ds_bpermute_b32 v7, v7, v146 offset:4
	v_mov_b32_e32 v163, v5
	s_waitcnt lgkmcnt(1)
	v_pk_mul_f32 v[70:71], v[70:71], v[144:145]
	s_waitcnt lgkmcnt(0)
	v_pk_mul_f32 v[68:69], v[68:69], v[6:7]
	v_pk_mul_f32 v[66:67], v[66:67], v[144:145]
	v_pk_mul_f32 v[64:65], v[64:65], v[6:7]
	v_pk_mul_f32 v[62:63], v[62:63], v[144:145]
	v_pk_mul_f32 v[60:61], v[60:61], v[6:7]
	v_pk_mul_f32 v[58:59], v[58:59], v[144:145]
	v_pk_mul_f32 v[56:57], v[56:57], v[6:7]
	v_pk_mul_f32 v[74:75], v[74:75], v[144:145]
	v_pk_mul_f32 v[72:73], v[72:73], v[6:7]

.LBB0_147:
	v_max3_f32 v5, v136, v137, v138
	s_nop 3
	v_max3_f32 v6, v139, v140, v141
	v_max_f32_e32 v7, v142, v143
	v_max3_f32 v5, v5, v6, v7
	v_add_f32_e32 v6, 0x41000000, v158
	v_cmp_gt_f32_e32 vcc, v5, v6
	s_cbranch_vccz .LBB0_149
	v_and_b32_e32 v7, 64, v192
	v_xor_b32_e32 v6, 16, v192
	v_add_u32_e32 v144, 64, v7
	v_cmp_lt_i32_e32 vcc, v6, v144
	v_xor_b32_e32 v145, 32, v192
	s_nop 0
	v_cndmask_b32_e32 v6, v192, v6, vcc
	v_lshlrev_b32_e32 v6, 2, v6
	ds_bpermute_b32 v6, v6, v5
	v_max_f32_e32 v5, v5, v5
	v_cmp_lt_i32_e32 vcc, v145, v144
	s_waitcnt lgkmcnt(0)
	v_max_f32_e32 v6, v6, v6
	v_max_f32_e32 v5, v5, v6
	v_cndmask_b32_e32 v6, v192, v145, vcc
	v_lshlrev_b32_e32 v6, 2, v6
	ds_bpermute_b32 v6, v6, v5
	s_waitcnt lgkmcnt(0)
	v_max3_f32 v5, v158, v5, v6
	v_sub_f32_e32 v6, v158, v5
	v_exp_f32_e32 v146, v6
	v_or_b32_e32 v6, v7, v167
	v_lshlrev_b32_e32 v7, 2, v6
	v_or_b32_e32 v145, 12, v7
	ds_bpermute_b32 v6, v7, v146
	ds_bpermute_b32 v144, v7, v146 offset:8
	ds_bpermute_b32 v145, v145, v146
	ds_bpermute_b32 v7, v7, v146 offset:4
	v_mov_b32_e32 v158, v5
	s_waitcnt lgkmcnt(1)
	v_pk_mul_f32 v[50:51], v[50:51], v[144:145]
	s_waitcnt lgkmcnt(0)
	v_pk_mul_f32 v[48:49], v[48:49], v[6:7]
	v_pk_mul_f32 v[46:47], v[46:47], v[144:145]
	v_pk_mul_f32 v[44:45], v[44:45], v[6:7]
	v_pk_mul_f32 v[42:43], v[42:43], v[144:145]
	v_pk_mul_f32 v[40:41], v[40:41], v[6:7]
	v_pk_mul_f32 v[38:39], v[38:39], v[144:145]
	v_pk_mul_f32 v[36:37], v[36:37], v[6:7]
	v_pk_mul_f32 v[54:55], v[54:55], v[144:145]
	v_pk_mul_f32 v[52:53], v[52:53], v[6:7]

.LBB0_157:
	v_max3_f32 v5, v128, v129, v130
	s_nop 3
	v_max3_f32 v6, v131, v120, v121
	v_max_f32_e32 v7, v122, v123
	v_max3_f32 v5, v5, v6, v7
	v_add_f32_e32 v6, 0x41000000, v159
	v_cmp_gt_f32_e32 vcc, v5, v6
	s_cbranch_vccz .LBB0_118
	v_and_b32_e32 v7, 64, v192
	v_xor_b32_e32 v6, 16, v192
	v_add_u32_e32 v124, 64, v7
	v_cmp_lt_i32_e32 vcc, v6, v124
	v_xor_b32_e32 v125, 32, v192
	s_nop 0
	v_cndmask_b32_e32 v6, v192, v6, vcc
	v_lshlrev_b32_e32 v6, 2, v6
	ds_bpermute_b32 v6, v6, v5
	v_max_f32_e32 v5, v5, v5
	v_cmp_lt_i32_e32 vcc, v125, v124
	s_waitcnt lgkmcnt(0)
	v_max_f32_e32 v6, v6, v6
	v_max_f32_e32 v5, v5, v6
	v_cndmask_b32_e32 v6, v192, v125, vcc
	v_lshlrev_b32_e32 v6, 2, v6
	ds_bpermute_b32 v6, v6, v5
	s_waitcnt lgkmcnt(0)
	v_max3_f32 v5, v159, v5, v6
	v_sub_f32_e32 v6, v159, v5
	v_exp_f32_e32 v126, v6
	v_or_b32_e32 v6, v7, v167
	v_lshlrev_b32_e32 v7, 2, v6
	v_or_b32_e32 v125, 12, v7
	ds_bpermute_b32 v6, v7, v126
	ds_bpermute_b32 v124, v7, v126 offset:8
	ds_bpermute_b32 v125, v125, v126
	ds_bpermute_b32 v7, v7, v126 offset:4
	v_mov_b32_e32 v159, v5
	s_waitcnt lgkmcnt(1)
	v_pk_mul_f32 v[30:31], v[30:31], v[124:125]
	s_waitcnt lgkmcnt(0)
	v_pk_mul_f32 v[28:29], v[28:29], v[6:7]
	v_pk_mul_f32 v[26:27], v[26:27], v[124:125]
	v_pk_mul_f32 v[24:25], v[24:25], v[6:7]
	v_pk_mul_f32 v[22:23], v[22:23], v[124:125]
	v_pk_mul_f32 v[20:21], v[20:21], v[6:7]
	v_pk_mul_f32 v[18:19], v[18:19], v[124:125]
	v_pk_mul_f32 v[16:17], v[16:17], v[6:7]
	v_pk_mul_f32 v[34:35], v[34:35], v[124:125]
	v_pk_mul_f32 v[32:33], v[32:33], v[6:7]
	s_branch .LBB0_118
